# attention passes: next pass's Q fragments and first K half-tile requested before the current finalize (first pass: before the bias-table load)
# baseline (speedup 1.0000x reference)
.LBB0_251:
	s_load_dwordx2 s[8:9], s[36:37], 0xa8
	s_mov_b32 s44, s18
	s_sub_i32 s0, s18, 0x1c2
	s_cmp_lt_i32 s0, 39
	s_cbranch_scc1 .Lpfr_done0
	s_cmp_gt_i32 s0, 48
	s_cbranch_scc1 .Lpfr_hi0
	s_cmp_eq_u32 s0, 42
	s_cbranch_scc1 .Lpfr_done0
	s_cmp_eq_u32 s0, 46
	s_cbranch_scc1 .Lpfr_done0
	s_sub_i32 s1, s0, 39
	s_cmp_gt_i32 s0, 42
	s_cselect_b32 s5, 1, 0
	s_sub_i32 s1, s1, s5
	s_cmp_gt_i32 s0, 46
	s_cselect_b32 s5, 1, 0
	s_sub_i32 s1, s1, s5
	s_add_i32 s44, s1, 0x200
	s_branch .Lpfr_done0
.Lpfr_hi0:
	s_cmp_lt_i32 s0, 62
	s_cbranch_scc1 .Lpfr_done0
	s_sub_i32 s1, s0, 62
	s_cmp_gt_i32 s1, 2
	s_cselect_b32 s5, 1, 0
	s_add_i32 s6, s1, s5
	s_cmp_gt_i32 s1, 5
	s_cselect_b32 s5, 1, 0
	s_add_i32 s6, s6, s5
	s_add_i32 s44, s6, 0x1e9
.Lpfr_done0:
	s_waitcnt lgkmcnt(0)
	s_mov_b32 s43, 0
	s_cmpk_ge_i32 s44, 0x200
	s_cbranch_scc1 .Lpf_skip1
	s_mov_b32 s43, 1
	s_movk_i32 s6, 0x1c00
	s_bfe_u32 s45, s44, 0x70001
	s_lshr_b32 s46, s44, 8
	s_lshl_b32 s46, s46, 13
	s_lshl_b32 s0, s45, 6
	s_or_b32 s0, s0, s46
	s_mul_i32 s0, s0, 0x1c00
	s_add_i32 s0, s0, 0x6000000
	s_add_u32 s0, s8, s0
	s_addc_u32 s1, s9, 0
	s_and_b32 s5, s44, 1
	s_lshl_b32 s5, s5, 5
	v_and_b32_e32 v130, 31, v224
	v_add_u32_e32 v130, s5, v130
	v_mul_u32_u24_e32 v130, 0x1c00, v130
	v_and_b32_e32 v131, 0x3c0, v224
	v_bfe_u32 v132, v224, 5, 1
	v_lshlrev_b32_e32 v131, 1, v131
	v_lshlrev_b32_e32 v132, 4, v132
	v_add3_u32 v130, v130, v131, v132
	global_load_dwordx4 v[64:67], v130, s[0:1]
	global_load_dwordx4 v[68:71], v130, s[0:1] offset:32
	global_load_dwordx4 v[72:75], v130, s[0:1] offset:64
	global_load_dwordx4 v[76:79], v130, s[0:1] offset:96
	s_sub_i32 s5, 8, s45
	s_max_i32 s5, s5, 0
	s_add_i32 s5, s5, s45
	s_add_i32 s5, s5, -8
	s_lshl_b32 s5, s5, 6
	s_add_i32 s5, s5, s46
	s_mul_i32 s5, s5, 0x1c00
	s_add_i32 s5, s5, 0x6000000
	s_add_u32 s0, s8, s5
	s_addc_u32 s1, s9, 0
	v_bfe_u32 v132, v224, 3, 3
	v_and_b32_e32 v133, 7, v224
	v_mad_u32_u24 v131, v132, s6, v131
	v_lshl_add_u32 v131, v133, 4, v131
	v_add_u32_e32 v131, 0x400, v131
	global_load_dwordx4 v[80:83], v131, s[0:1]
	s_add_u32 s0, s0, 0xe000
	s_addc_u32 s1, s1, 0
	global_load_dwordx4 v[84:87], v131, s[0:1]
	s_add_u32 s0, s0, 0xe000
	s_addc_u32 s1, s1, 0
	global_load_dwordx4 v[88:91], v131, s[0:1]
	s_add_u32 s0, s0, 0xe000
	s_addc_u32 s1, s1, 0
	global_load_dwordx4 v[92:95], v131, s[0:1]

.Lrd_done:
	s_lshl_b32 s22, s18, 5
	s_lshl_b32 s26, s18, 3
	s_add_i32 s26, s26, 0xfffff000
	s_cmpk_lt_i32 s18, 0x200
	s_mov_b64 s[0:1], -1
	s_cbranch_scc0 .LBB0_285
	s_mov_b64 s[8:9], s[36:37]
	v_mov_b32_e32 v12, v224
	s_load_dwordx2 s[2:3], s[8:9], 0xa8
	s_and_b32 s6, s22, 0xffffe000
	s_bfe_u32 s7, s18, 0x70001
	v_ashrrev_i32_e32 v0, 6, v12
	s_movk_i32 s4, 0x2400
	s_waitcnt lgkmcnt(0)
	s_add_u32 s0, s2, 0x6000000
	s_addc_u32 s1, s3, 0
	v_mul_lo_u32 v4, v0, s4
	s_lshl_b32 s4, s18, 5
	v_and_b32_e32 v252, 31, v12
	v_mul_lo_u32 v0, v0, s61
	s_and_b32 s11, s4, 0xffffe000
	s_lshl_b32 s5, s7, 6
	s_and_b32 s10, s4, 32
	v_add_u32_e32 v246, s19, v0
	s_or_b32 s5, s5, s11
	v_or_b32_e32 v0, s10, v252
	s_waitcnt vmcnt(10)
	v_or_b32_e32 v162, s5, v0
	v_mov_b64_e32 v[0:1], s[0:1]
	s_movk_i32 s4, 0x1c00
	v_mad_i64_i32 v[0:1], s[4:5], v162, s4, v[0:1]
	s_sub_i32 s4, 8, s7
	s_cmp_lt_u32 s7, 8
	s_cselect_b32 s29, s4, 0
	s_add_i32 s4, s29, s7
	s_lshl_b32 s7, s4, 6
	v_and_b32_e32 v164, 0xffffffc0, v12
	s_add_i32 s4, s11, s7
	v_ashrrev_i32_e32 v165, 31, v164
	s_addk_i32 s4, 0xfe00
	v_bfe_u32 v13, v12, 5, 1
	v_lshlrev_b64 v[2:3], 1, v[164:165]
	s_mul_hi_i32 s5, s4, 0x1c00
	s_mulk_i32 s4, 0x1c00
	v_lshl_add_u64 v[0:1], v[0:1], 0, v[2:3]
	v_lshlrev_b32_e32 v112, 4, v13
	s_add_u32 s4, s0, s4
	v_lshl_add_u64 v[0:1], v[0:1], 0, v[112:113]
	v_add_u32_e32 v15, s24, v4
	s_addc_u32 s5, s1, s5
	v_mul_u32_u24_e32 v4, 0xe00, v252
	s_cmp_eq_u32 s43, 1
	s_cbranch_scc1 .Lpf_q_done
	global_load_dwordx4 v[64:67], v[0:1], off
	global_load_dwordx4 v[68:71], v[0:1], off offset:32
	global_load_dwordx4 v[72:75], v[0:1], off offset:64
	global_load_dwordx4 v[76:79], v[0:1], off offset:96
.Lpf_q_done:
	v_lshl_add_u64 v[0:1], s[4:5], 0, v[2:3]
	v_lshlrev_b32_e32 v4, 1, v4
	v_mov_b32_e32 v5, v113
	v_lshl_add_u64 v[6:7], v[0:1], 0, v[4:5]
	v_lshl_add_u64 v[6:7], v[6:7], 0, v[112:113]
	ds_read_b32 v166, v246 offset:1276
	v_bfe_u32 v216, v12, 3, 3
	v_and_b32_e32 v217, 7, v12
	v_lshlrev_b32_e32 v213, 1, v164
	v_mad_u32_u24 v213, v216, v238, v213
	v_lshl_add_u32 v213, v217, 4, v213
	v_add_u32_e32 v213, 0x400, v213
	v_mul_u32_u24_e32 v214, 0x48, v164
	v_add_u32_e32 v214, 0x15000, v214
	v_add_u32_e32 v214, s24, v214
	v_mul_u32_u24_e32 v215, 0x90, v252
	v_lshl_add_u32 v215, v13, 4, v215
	v_add_u32_e32 v215, v215, v214
	v_mul_u32_u24_e32 v218, 0x90, v216
	v_lshl_add_u32 v218, v217, 4, v218
	v_add_u32_e32 v214, v214, v218
	s_mov_b64 s[38:39], s[4:5]
	s_cmp_eq_u32 s43, 1
	s_cbranch_scc1 .Lpf_k_skip
	global_load_dwordx4 v[80:83], v213, s[38:39]
	s_add_u32 s38, s38, 0xe000
	s_addc_u32 s39, s39, 0
	global_load_dwordx4 v[84:87], v213, s[38:39]
	s_add_u32 s38, s38, 0xe000
	s_addc_u32 s39, s39, 0
	global_load_dwordx4 v[88:91], v213, s[38:39]
	s_add_u32 s38, s38, 0xe000
	s_addc_u32 s39, s39, 0
	global_load_dwordx4 v[92:95], v213, s[38:39]
	s_branch .Lpf_k_done
.Lpf_k_skip:
	s_add_u32 s38, s38, 0x2a000
	s_addc_u32 s39, s39, 0
.Lpf_k_done:
	s_mov_b32 s43, 0
	s_add_u32 s38, s38, 0xe000
	s_addc_u32 s39, s39, 0
	v_bfe_u32 v16, v12, 3, 3
	v_lshlrev_b32_e32 v6, 4, v12
	v_and_b32_e32 v6, 0x70, v6
	v_mov_b32_e32 v7, v113
	v_mul_u32_u24_e32 v34, 0xe00, v16
	v_lshl_add_u64 v[0:1], v[0:1], 0, v[6:7]
	v_lshlrev_b32_e32 v8, 1, v34
	v_mov_b32_e32 v9, v113
	v_lshl_add_u64 v[8:9], v[0:1], 0, v[8:9]
	s_mov_b32 s4, 0xe000
	v_add_co_u32_e32 v10, vcc, s4, v8
	s_mov_b32 s4, 0x1c000
	s_nop 0
	v_addc_co_u32_e32 v11, vcc, 0, v9, vcc
	global_load_dwordx4 v[96:99], v[8:9], off offset:2048
	global_load_dwordx4 v[100:103], v[10:11], off offset:2048
	v_add_co_u32_e32 v10, vcc, s4, v8
	s_mov_b32 s4, 0x2a000
	s_nop 0
	v_addc_co_u32_e32 v11, vcc, 0, v9, vcc
	v_add_co_u32_e32 v8, vcc, s4, v8
	s_movk_i32 s4, 0xe00
	s_nop 0
	v_addc_co_u32_e32 v9, vcc, 0, v9, vcc
	global_load_dwordx4 v[104:107], v[10:11], off offset:2048
	global_load_dwordx4 v[108:111], v[8:9], off offset:2048
	v_mov_b32_e32 v8, 0x1c000
	v_mad_u32_u24 v36, v16, s4, v8
	v_mov_b32_e32 v10, 0x23000
	v_lshlrev_b32_e32 v8, 1, v36
	v_mov_b32_e32 v9, v113
	v_mad_u32_u24 v38, v16, s4, v10
	v_lshl_add_u64 v[8:9], v[0:1], 0, v[8:9]
	v_lshlrev_b32_e32 v10, 1, v38
	v_mov_b32_e32 v11, v113
	v_lshl_add_u64 v[10:11], v[0:1], 0, v[10:11]
	global_load_dwordx4 v[114:117], v[8:9], off offset:2048
	global_load_dwordx4 v[118:121], v[10:11], off offset:2048
	v_mov_b32_e32 v8, 0x2a000
	v_mad_u32_u24 v40, v16, s4, v8
	v_mov_b32_e32 v10, 0x31000
	v_lshlrev_b32_e32 v8, 1, v40
	v_mov_b32_e32 v9, v113
	v_mad_u32_u24 v42, v16, s4, v10
	v_lshl_add_u64 v[8:9], v[0:1], 0, v[8:9]
	v_lshlrev_b32_e32 v10, 1, v42
	v_mov_b32_e32 v11, v113
	v_lshl_add_u64 v[0:1], v[0:1], 0, v[10:11]
	global_load_dwordx4 v[122:125], v[8:9], off offset:2048
	global_load_dwordx4 v[126:129], v[0:1], off offset:2048
	global_load_dwordx4 v[146:149], v213, s[38:39]
	s_add_u32 s38, s38, 0xe000
	s_addc_u32 s39, s39, 0
	global_load_dwordx4 v[150:153], v213, s[38:39]
	s_add_u32 s38, s38, 0xe000
	s_addc_u32 s39, s39, 0
	global_load_dwordx4 v[154:157], v213, s[38:39]
	s_add_u32 s38, s38, 0xe000
	s_addc_u32 s39, s39, 0
	global_load_dwordx4 v[158:161], v213, s[38:39]
	v_lshrrev_b32_e32 v14, 2, v12
	v_lshl_add_u64 v[0:1], s[0:1], 0, v[2:3]
	v_lshlrev_b32_e32 v199, 2, v13
	v_lshlrev_b32_e32 v17, 3, v12
	v_lshl_add_u64 v[168:169], v[0:1], 0, v[4:5]
	v_and_or_b32 v2, v14, 3, v199
	v_lshlrev_b32_e32 v3, 1, v12
	v_lshl_add_u64 v[184:185], v[0:1], 0, v[6:7]
	v_and_or_b32 v0, s22, 32, v252
	v_mul_u32_u24_e32 v2, 0x90, v2
	v_and_b32_e32 v35, 32, v3
	v_and_b32_e32 v3, 24, v17
	s_add_i32 s0, s6, s7
	v_or_b32_e32 v0, 0x200, v0
	v_lshlrev_b32_e32 v32, 3, v13
	v_add_u32_e32 v33, v15, v6
	v_add3_u32 v37, v15, v2, v3
	v_mul_u32_u24_e32 v39, 0x90, v16
	s_add_i32 s11, s0, 0xfffffe00
	v_sub_u32_e32 v0, v0, v199
	s_lshl_b32 s0, s29, 6
	v_mov_b32_e32 v251, 0
	v_mov_b32_e32 v248, v224
	v_and_b32_e32 v232, 63, v12
	v_ashrrev_i32_e32 v163, 31, v162
	s_waitcnt lgkmcnt(0)
	v_mov_b32_e32 v167, v166
	v_mov_b32_e32 v170, v166
	v_mov_b32_e32 v171, v166
	v_mov_b32_e32 v172, v166
	v_mov_b32_e32 v173, v166
	v_mov_b32_e32 v174, v166
	v_mov_b32_e32 v175, v166
	v_mov_b32_e32 v176, v166
	v_mov_b32_e32 v177, v166
	v_mov_b32_e32 v178, v166
	v_mov_b32_e32 v179, v166
	v_mov_b32_e32 v180, v166
	v_mov_b32_e32 v181, v166
	v_mov_b32_e32 v182, v166
	v_mov_b32_e32 v183, v166
	v_lshl_add_u64 v[186:187], v[168:169], 0, v[112:113]
	s_add_i32 s28, s29, -1
	v_subrev_u32_e32 v247, s0, v0
	v_mov_b32_e32 v16, v113
	v_mov_b32_e32 v17, v113
	v_mov_b32_e32 v18, v113
	v_mov_b32_e32 v19, v113
	v_mov_b32_e32 v20, v113
	v_mov_b32_e32 v21, v113
	v_mov_b32_e32 v22, v113
	v_mov_b32_e32 v23, v113
	v_mov_b32_e32 v24, v113
	v_mov_b32_e32 v25, v113
	v_mov_b32_e32 v26, v113
	v_mov_b32_e32 v27, v113
	v_mov_b32_e32 v28, v113
	v_mov_b32_e32 v29, v113
	v_mov_b32_e32 v30, v113
	v_mov_b32_e32 v31, v113
	v_mov_b32_e32 v0, v113
	v_mov_b32_e32 v1, v113
	v_mov_b32_e32 v2, v113
	v_mov_b32_e32 v3, v113
	v_mov_b32_e32 v4, v113
	v_mov_b32_e32 v6, v113
	v_mov_b32_e32 v8, v113
	v_mov_b32_e32 v9, v113
	v_mov_b32_e32 v10, v113
	v_mov_b32_e32 v12, v113
	v_mov_b32_e32 v13, v113
	v_mov_b32_e32 v14, v113
	v_mov_b32_e32 v15, v113
	v_mov_b32_e32 v233, 0xf149f2ca
	v_add_u32_e32 v245, v33, v39
	v_lshlrev_b32_e32 v188, 1, v34
	v_lshlrev_b32_e32 v190, 1, v36
	v_lshlrev_b32_e32 v192, 1, v38
	v_lshlrev_b32_e32 v194, 1, v40
	v_lshlrev_b32_e32 v196, 1, v42
	v_lshlrev_b32_e32 v112, 1, v32
	v_add_u32_e32 v250, v37, v35
	s_waitcnt vmcnt(12)
	ds_write_b128 v214, v[80:83]
	ds_write_b128 v214, v[84:87] offset:1152
	ds_write_b128 v214, v[88:91] offset:2304
	ds_write_b128 v214, v[92:95] offset:3456

.LBB0_282:
	s_load_dwordx2 s[40:41], s[8:9], 0x68
	v_add_lshl_u32 v193, v164, v199, 2
	s_lshl_b32 s4, s21, 2
	v_mov_b32_e32 v32, v251
	s_nop 1
	v_permlane32_swap_b32_e32 v32, v251
	s_waitcnt lgkmcnt(0)
	s_add_u32 s40, s40, s4
	s_addc_u32 s41, s41, 0
	global_load_dwordx4 v[126:129], v193, s[40:41]
	global_load_dwordx4 v[96:99], v193, s[40:41] offset:32
	global_load_dwordx4 v[100:103], v193, s[40:41] offset:64
	global_load_dwordx4 v[104:107], v193, s[40:41] offset:96
	global_load_dwordx4 v[108:111], v193, s[40:41] offset:128
	global_load_dwordx4 v[114:117], v193, s[40:41] offset:160
	global_load_dwordx4 v[118:121], v193, s[40:41] offset:192
	global_load_dwordx4 v[122:125], v193, s[40:41] offset:224
	s_add_i32 s45, s32, s13
	s_mov_b32 s43, 0
	s_mov_b32 s44, s18
	s_cmp_ge_i32 s45, s15
	s_cbranch_scc1 .Lpf_go2
	s_mov_b32 s46, s45
	s_sub_i32 s0, s45, 0x1c2
	s_cmp_lt_i32 s0, 39
	s_cbranch_scc1 .Lpfr_done1
	s_cmp_gt_i32 s0, 48
	s_cbranch_scc1 .Lpfr_hi1
	s_cmp_eq_u32 s0, 42
	s_cbranch_scc1 .Lpfr_done1
	s_cmp_eq_u32 s0, 46
	s_cbranch_scc1 .Lpfr_done1
	s_sub_i32 s1, s0, 39
	s_cmp_gt_i32 s0, 42
	s_cselect_b32 s5, 1, 0
	s_sub_i32 s1, s1, s5
	s_cmp_gt_i32 s0, 46
	s_cselect_b32 s5, 1, 0
	s_sub_i32 s1, s1, s5
	s_add_i32 s46, s1, 0x200
	s_branch .Lpfr_done1
.Lpfr_hi1:
	s_cmp_lt_i32 s0, 62
	s_cbranch_scc1 .Lpfr_done1
	s_sub_i32 s1, s0, 62
	s_cmp_gt_i32 s1, 2
	s_cselect_b32 s5, 1, 0
	s_add_i32 s6, s1, s5
	s_cmp_gt_i32 s1, 5
	s_cselect_b32 s5, 1, 0
	s_add_i32 s6, s6, s5
	s_add_i32 s46, s6, 0x1e9
.Lpfr_done1:
	s_cmpk_ge_i32 s46, 0x200
	s_cbranch_scc1 .Lpf_go2
	s_mov_b32 s44, s46
	s_mov_b32 s43, 1
.Lpf_go2:
	s_movk_i32 s6, 0x1c00
	s_bfe_u32 s45, s44, 0x70001
	s_lshr_b32 s46, s44, 8
	s_lshl_b32 s46, s46, 13
	s_lshl_b32 s0, s45, 6
	s_or_b32 s0, s0, s46
	s_mul_i32 s0, s0, 0x1c00
	s_add_i32 s0, s0, 0x6000000
	s_add_u32 s0, s2, s0
	s_addc_u32 s1, s3, 0
	s_and_b32 s5, s44, 1
	s_lshl_b32 s5, s5, 5
	v_and_b32_e32 v130, 31, v248
	v_add_u32_e32 v130, s5, v130
	v_mul_u32_u24_e32 v130, 0x1c00, v130
	v_and_b32_e32 v131, 0x3c0, v248
	v_bfe_u32 v132, v248, 5, 1
	v_lshlrev_b32_e32 v131, 1, v131
	v_lshlrev_b32_e32 v132, 4, v132
	v_add3_u32 v130, v130, v131, v132
	global_load_dwordx4 v[64:67], v130, s[0:1]
	global_load_dwordx4 v[68:71], v130, s[0:1] offset:32
	global_load_dwordx4 v[72:75], v130, s[0:1] offset:64
	global_load_dwordx4 v[76:79], v130, s[0:1] offset:96
	s_sub_i32 s5, 8, s45
	s_max_i32 s5, s5, 0
	s_add_i32 s5, s5, s45
	s_add_i32 s5, s5, -8
	s_lshl_b32 s5, s5, 6
	s_add_i32 s5, s5, s46
	s_mul_i32 s5, s5, 0x1c00
	s_add_i32 s5, s5, 0x6000000
	s_add_u32 s0, s2, s5
	s_addc_u32 s1, s3, 0
	v_bfe_u32 v132, v248, 3, 3
	v_and_b32_e32 v133, 7, v248
	v_mad_u32_u24 v131, v132, s6, v131
	v_lshl_add_u32 v131, v133, 4, v131
	v_add_u32_e32 v131, 0x400, v131
	global_load_dwordx4 v[80:83], v131, s[0:1]
	s_add_u32 s0, s0, 0xe000
	s_addc_u32 s1, s1, 0
	global_load_dwordx4 v[84:87], v131, s[0:1]
	s_add_u32 s0, s0, 0xe000
	s_addc_u32 s1, s1, 0
	global_load_dwordx4 v[88:91], v131, s[0:1]
	s_add_u32 s0, s0, 0xe000
	s_addc_u32 s1, s1, 0
	global_load_dwordx4 v[92:95], v131, s[0:1]
	v_add_f32_e32 v32, v251, v32
	v_div_scale_f32 v33, s[0:1], v32, v32, 1.0
	v_rcp_f32_e32 v34, v33
	v_div_scale_f32 v35, vcc, 1.0, v32, 1.0
	v_fma_f32 v36, -v33, v34, 1.0
	v_fmac_f32_e32 v34, v36, v34
	v_mul_f32_e32 v36, v35, v34
	v_fma_f32 v37, -v33, v36, v35
	v_fmac_f32_e32 v36, v37, v34
	v_fma_f32 v33, -v33, v36, v35
	v_div_fmas_f32 v33, v33, v34, v36
	v_div_fixup_f32 v36, v33, v32, 1.0
	v_pk_mul_f32 v[34:35], v[16:17], v[36:37] op_sel_hi:[1,0]
	v_pk_mul_f32 v[32:33], v[18:19], v[36:37] op_sel_hi:[1,0]
	v_mul_f32_e32 v16, v35, v35
	v_fmac_f32_e32 v16, v34, v34
	v_fmac_f32_e32 v16, v32, v32
	v_pk_mul_f32 v[20:21], v[20:21], v[36:37] op_sel_hi:[1,0]
	v_fmac_f32_e32 v16, v33, v33
	v_fmac_f32_e32 v16, v20, v20
	v_pk_mul_f32 v[22:23], v[22:23], v[36:37] op_sel_hi:[1,0]
	v_fmac_f32_e32 v16, v21, v21
	v_fmac_f32_e32 v16, v22, v22
	v_pk_mul_f32 v[24:25], v[24:25], v[36:37] op_sel_hi:[1,0]
	v_fmac_f32_e32 v16, v23, v23
	v_fmac_f32_e32 v16, v24, v24
	v_pk_mul_f32 v[26:27], v[26:27], v[36:37] op_sel_hi:[1,0]
	v_fmac_f32_e32 v16, v25, v25
	v_fmac_f32_e32 v16, v26, v26
	v_pk_mul_f32 v[28:29], v[28:29], v[36:37] op_sel_hi:[1,0]
	v_fmac_f32_e32 v16, v27, v27
	v_fmac_f32_e32 v16, v28, v28
	v_pk_mul_f32 v[30:31], v[30:31], v[36:37] op_sel_hi:[1,0]
	v_fmac_f32_e32 v16, v29, v29
	v_fmac_f32_e32 v16, v30, v30
	v_fmac_f32_e32 v16, v31, v31
	v_pk_mul_f32 v[0:1], v[0:1], v[36:37] op_sel_hi:[1,0]
	v_pk_mul_f32 v[2:3], v[2:3], v[36:37] op_sel_hi:[1,0]
	v_fmac_f32_e32 v16, v0, v0
	v_fmac_f32_e32 v16, v1, v1
	v_fmac_f32_e32 v16, v2, v2
	v_pk_mul_f32 v[4:5], v[4:5], v[36:37] op_sel_hi:[1,0]
	v_fmac_f32_e32 v16, v3, v3
	v_fmac_f32_e32 v16, v4, v4
	v_pk_mul_f32 v[6:7], v[6:7], v[36:37] op_sel_hi:[1,0]
	v_fmac_f32_e32 v16, v5, v5
	v_fmac_f32_e32 v16, v6, v6
	v_pk_mul_f32 v[8:9], v[8:9], v[36:37] op_sel_hi:[1,0]
	v_fmac_f32_e32 v16, v7, v7
	v_fmac_f32_e32 v16, v8, v8
	v_pk_mul_f32 v[10:11], v[10:11], v[36:37] op_sel_hi:[1,0]
	v_fmac_f32_e32 v16, v9, v9
	v_fmac_f32_e32 v16, v10, v10
	v_pk_mul_f32 v[12:13], v[12:13], v[36:37] op_sel_hi:[1,0]
	v_fmac_f32_e32 v16, v11, v11
	v_fmac_f32_e32 v16, v12, v12
	v_pk_mul_f32 v[14:15], v[14:15], v[36:37] op_sel_hi:[1,0]
	v_fmac_f32_e32 v16, v13, v13
	v_fmac_f32_e32 v16, v14, v14
	v_fmac_f32_e32 v16, v15, v15
	v_mov_b32_e32 v17, v16
	s_nop 1
	v_permlane32_swap_b32_e32 v17, v16
	v_cmp_gt_u32_e32 vcc, 32, v232
	s_and_saveexec_b64 s[0:1], vcc
	s_cbranch_execz .LBB0_284
	s_lshl_b32 s4, s10, 2
	v_lshlrev_b32_e32 v18, 2, v164
	s_add_i32 s4, s4, s20
	v_lshlrev_b32_e32 v19, 2, v252
	v_add3_u32 v18, s4, v18, v19
	v_add_f32_e32 v16, v16, v17
	ds_write_b32 v18, v16
	.LBB0_284:
	s_or_b64 exec, exec, s[0:1]
	s_waitcnt lgkmcnt(0)
	s_barrier
	v_mov_b32_e32 v225, 0x358637bd
	v_mov_b32_e32 v226, 0x260
	v_lshlrev_b32_e32 v112, 2, v199
	s_lshl_b32 s4, s10, 2
	s_add_i32 s4, s20, s4
	v_lshl_add_u32 v18, v252, 2, s4
	ds_read2st64_b32 v[16:17], v18 offset1:1
	ds_read2st64_b32 v[36:37], v18 offset0:2 offset1:3
	ds_read2st64_b32 v[38:39], v18 offset0:4 offset1:5
	ds_read2st64_b32 v[40:41], v18 offset0:6 offset1:7
	v_mov_b32_e32 v224, v248
	v_add_u32_e32 v227, -1, v236
	v_add_u32_e32 v228, -2, v236
	v_add_u32_e32 v229, -4, v236
	v_add_u32_e32 v230, -8, v236
	v_add_u32_e32 v231, -16, v236
	v_subrev_u32_e32 v232, 32, v236
	v_bfrev_b32_e32 v233, 0.5
	v_mov_b32_e32 v234, 0x1400
	v_mov_b32_e32 v235, 0x1000
	v_mov_b32_e32 v239, 0xf800000
	v_mov_b32_e32 v240, 0xf400000
	s_waitcnt lgkmcnt(0)
	v_add_f32_e32 v16, 0, v16
	v_add_f32_e32 v19, v16, v17
	v_add_f32_e32 v16, v19, v36
	v_add_f32_e32 v19, v16, v37
	v_add_f32_e32 v16, v19, v38
	v_add_f32_e32 v19, v16, v39
	v_add_f32_e32 v16, v19, v40
	v_add_f32_e32 v16, v16, v41
	v_fmamk_f32 v16, v16, 0x3b000000, v225
	s_mov_b32 s0, 0xf800000
	v_cmp_gt_f32_e32 vcc, s0, v16
	v_mul_f32_e32 v17, 0x4f800000, v16
	v_cndmask_b32_e32 v16, v16, v17, vcc
	v_sqrt_f32_e32 v17, v16
	v_lshlrev_b32_e32 v112, 1, v199
	v_add_u32_e32 v36, -1, v17
	v_fma_f32 v37, -v36, v17, v16
	v_cmp_ge_f32_e64 s[38:39], 0, v37
	v_add_u32_e32 v37, 1, v17
	s_nop 0
	v_cndmask_b32_e64 v36, v17, v36, s[38:39]
	v_fma_f32 v17, -v37, v17, v16
	v_cmp_lt_f32_e64 s[38:39], 0, v17
	s_nop 1
	v_cndmask_b32_e64 v17, v36, v37, s[38:39]
	v_mul_f32_e32 v36, 0x37800000, v17
	v_cndmask_b32_e32 v17, v17, v36, vcc
	v_cmp_class_f32_e32 vcc, v16, v226
	s_nop 1
	v_cndmask_b32_e32 v16, v17, v16, vcc
	v_div_scale_f32 v17, s[0:1], v16, v16, 1.0
	v_rcp_f32_e32 v36, v17
	s_mov_b64 s[0:1], 0x1e00000
	v_fma_f32 v37, -v17, v36, 1.0
	v_fmac_f32_e32 v36, v37, v36
	v_div_scale_f32 v37, vcc, 1.0, v16, 1.0
	v_mul_f32_e32 v38, v37, v36
	v_fma_f32 v39, -v17, v38, v37
	v_fmac_f32_e32 v38, v39, v36
	v_fma_f32 v17, -v17, v38, v37
	v_div_fmas_f32 v17, v17, v36, v38
	v_lshlrev_b64 v[36:37], 11, v[162:163]
	v_div_fixup_f32 v16, v17, v16, 1.0
	v_lshl_add_u64 v[36:37], s[2:3], 0, v[36:37]
	v_lshl_add_u64 v[36:37], v[164:165], 1, v[36:37]
	v_pk_mul_f32 v[34:35], v[34:35], v[16:17] op_sel_hi:[1,0]
	v_pk_mul_f32 v[32:33], v[32:33], v[16:17] op_sel_hi:[1,0]
	v_lshl_add_u64 v[36:37], v[36:37], 0, v[112:113]
	v_pk_mul_f32 v[20:21], v[20:21], v[16:17] op_sel_hi:[1,0]
	v_pk_mul_f32 v[22:23], v[22:23], v[16:17] op_sel_hi:[1,0]
	v_pk_mul_f32 v[24:25], v[24:25], v[16:17] op_sel_hi:[1,0]
	v_pk_mul_f32 v[0:1], v[0:1], v[16:17] op_sel_hi:[1,0]
	v_pk_mul_f32 v[2:3], v[2:3], v[16:17] op_sel_hi:[1,0]
	v_pk_mul_f32 v[4:5], v[4:5], v[16:17] op_sel_hi:[1,0]
	s_waitcnt vmcnt(15)
	v_pk_mul_f32 v[34:35], v[126:127], v[34:35]
	v_pk_mul_f32 v[32:33], v[128:129], v[32:33]
	v_cvt_pk_bf16_f32 v34, v34, v35
	v_cvt_pk_bf16_f32 v35, v32, v33
	v_lshl_add_u64 v[32:33], v[36:37], 0, s[0:1]
	s_mov_b32 s0, 0x1e00000
	v_add_co_u32_e32 v36, vcc, s0, v36
	s_mov_b64 s[0:1], 0
	s_nop 0
	v_addc_co_u32_e32 v37, vcc, 0, v37, vcc
	global_store_dwordx2 v[36:37], v[34:35], off
	s_waitcnt vmcnt(15)
	v_pk_mul_f32 v[20:21], v[96:97], v[20:21]
	v_pk_mul_f32 v[22:23], v[98:99], v[22:23]
	v_cvt_pk_bf16_f32 v20, v20, v21
	v_cvt_pk_bf16_f32 v21, v22, v23
	global_store_dwordx2 v[32:33], v[20:21], off offset:16
	s_waitcnt vmcnt(15)
	v_pk_mul_f32 v[20:21], v[24:25], v[100:101]
	v_pk_mul_f32 v[24:25], v[26:27], v[16:17] op_sel_hi:[1,0]
	v_cvt_pk_bf16_f32 v20, v20, v21
	v_pk_mul_f32 v[22:23], v[24:25], v[102:103]
	v_pk_mul_f32 v[24:25], v[28:29], v[16:17] op_sel_hi:[1,0]
	v_cvt_pk_bf16_f32 v21, v22, v23
	global_store_dwordx2 v[32:33], v[20:21], off offset:32
	s_waitcnt vmcnt(15)
	v_pk_mul_f32 v[20:21], v[24:25], v[104:105]
	v_pk_mul_f32 v[24:25], v[30:31], v[16:17] op_sel_hi:[1,0]
	v_cvt_pk_bf16_f32 v20, v20, v21
	v_pk_mul_f32 v[22:23], v[24:25], v[106:107]
	s_nop 0
	v_cvt_pk_bf16_f32 v21, v22, v23
	global_store_dwordx2 v[32:33], v[20:21], off offset:48
	s_waitcnt vmcnt(15)
	v_pk_mul_f32 v[0:1], v[0:1], v[108:109]
	v_pk_mul_f32 v[2:3], v[2:3], v[110:111]
	v_cvt_pk_bf16_f32 v0, v0, v1
	v_cvt_pk_bf16_f32 v1, v2, v3
	global_store_dwordx2 v[32:33], v[0:1], off offset:64
	s_waitcnt vmcnt(15)
	v_pk_mul_f32 v[0:1], v[4:5], v[114:115]
	v_pk_mul_f32 v[4:5], v[6:7], v[16:17] op_sel_hi:[1,0]
	v_cvt_pk_bf16_f32 v0, v0, v1
	v_pk_mul_f32 v[2:3], v[4:5], v[116:117]
	v_pk_mul_f32 v[4:5], v[8:9], v[16:17] op_sel_hi:[1,0]
	v_cvt_pk_bf16_f32 v1, v2, v3
	global_store_dwordx2 v[32:33], v[0:1], off offset:80
	s_waitcnt vmcnt(15)
	v_pk_mul_f32 v[0:1], v[4:5], v[118:119]
	v_pk_mul_f32 v[4:5], v[10:11], v[16:17] op_sel_hi:[1,0]
	v_cvt_pk_bf16_f32 v0, v0, v1
	v_pk_mul_f32 v[2:3], v[4:5], v[120:121]
	v_pk_mul_f32 v[4:5], v[12:13], v[16:17] op_sel_hi:[1,0]
	v_cvt_pk_bf16_f32 v1, v2, v3
	global_store_dwordx2 v[32:33], v[0:1], off offset:96
	s_waitcnt vmcnt(15)
	v_pk_mul_f32 v[0:1], v[4:5], v[122:123]
	v_pk_mul_f32 v[4:5], v[14:15], v[16:17] op_sel_hi:[1,0]
	v_cvt_pk_bf16_f32 v0, v0, v1
	v_pk_mul_f32 v[2:3], v[4:5], v[124:125]
	s_nop 0
	v_cvt_pk_bf16_f32 v1, v2, v3
	global_store_dwordx2 v[32:33], v[0:1], off offset:112
	s_waitcnt vmcnt(8)
	s_barrier
